# hoisted ss loads in 3 bf16 epilogues + DPP-based MLA attention epilogue (no LDS round trips)
# speedup vs baseline: 1.0045x; 1.0045x over previous
; __device__ __forceinline__ unsigned cvt_pk_bf16(float lo, float hi) { unsigned r; asm volatile("v_cvt_pk_bf16_f32 %0, %1, %2" : "=v"(r) : "v"(lo), "v"(hi)); return r; }
;     __device__ __forceinline__ void operator()(const f32x4 (&acc)[2][2][4][2], const Unit& u, int wr, int wc, int fr, int fq) const {
;         const int row0 = u.pm * BM + wr * 64 + fr, col0 = u.pn * BM + wc * 32 + 8 * fq;
; #pragma unroll
;         for (int ai = 0; ai < 2; ++ai)
; #pragma unroll
;             for (int m = 0; m < 4; ++m) { const int row = row0 + ai * HALF + m * 16; bf16_t* rowp = O + (size_t)row * ldc + col0;
;                 const float rs = __builtin_amdgcn_rsqf(ss[row] * inv_n + EPS);
; #pragma unroll
;                 for (int bj = 0; bj < 2; ++bj) { const f32x4 v0 = acc[ai][bj][m][0] * rs, v1 = acc[ai][bj][m][1] * rs;
;                     u32x4 w; w.x = cvt_pk_bf16(v0[0], v0[1]); w.y = cvt_pk_bf16(v0[2], v0[3]); w.z = cvt_pk_bf16(v1[0], v1[1]); w.w = cvt_pk_bf16(v1[2], v1[3]);
;                     *(u32x4*)(rowp + bj * HALF) = w; } }
;     }
.LBB0_336:
	v_lshl_add_u32 v144, s28, 8, v165
	v_ashrrev_i32_e32 v145, 31, v144
	v_lshl_add_u64 v[150:151], v[144:145], 2, s[14:15]
	global_load_dword v184, v[150:151], off
	global_load_dword v185, v[150:151], off offset:64
	global_load_dword v186, v[150:151], off offset:128
	global_load_dword v187, v[150:151], off offset:192
	global_load_dword v188, v[150:151], off offset:512
	global_load_dword v189, v[150:151], off offset:576
	global_load_dword v190, v[150:151], off offset:640
	global_load_dword v191, v[150:151], off offset:704
	v_lshl_or_b32 v148, s52, 8, v167
	v_mov_b64_e32 v[146:147], s[12:13]
	v_ashrrev_i32_e32 v149, 31, v148
	v_mad_i64_i32 v[172:173], s[0:1], v144, s51, v[146:147]
	v_or_b32_e32 v174, 16, v144
	v_lshlrev_b64 v[148:149], 1, v[148:149]
	v_ashrrev_i32_e32 v175, 31, v174
	v_lshl_add_u64 v[172:173], v[172:173], 0, v[148:149]
	v_lshl_add_u64 v[178:179], v[174:175], 2, s[14:15]
	s_andn2_b64 vcc, exec, s[4:5]
	s_waitcnt vmcnt(0)
	v_fmamk_f32 v145, v184, 0x3b000000, v171
	v_rsq_f32_e32 v176, v145
	s_nop 0
	v_pk_mul_f32 v[126:127], v[126:127], v[176:177] op_sel_hi:[1,0]
	v_pk_mul_f32 v[124:125], v[124:125], v[176:177] op_sel_hi:[1,0]
	v_pk_mul_f32 v[122:123], v[122:123], v[176:177] op_sel_hi:[1,0]
	v_pk_mul_f32 v[120:121], v[120:121], v[176:177] op_sel_hi:[1,0]
	v_pk_mul_f32 v[118:119], v[118:119], v[176:177] op_sel_hi:[1,0]
	v_pk_mul_f32 v[116:117], v[116:117], v[176:177] op_sel_hi:[1,0]
	v_pk_mul_f32 v[180:181], v[114:115], v[176:177] op_sel_hi:[1,0]
	v_pk_mul_f32 v[176:177], v[112:113], v[176:177] op_sel_hi:[1,0]
	v_cvt_pk_bf16_f32 v112, v124, v125
	v_cvt_pk_bf16_f32 v113, v126, v127
	v_cvt_pk_bf16_f32 v114, v120, v121
	v_cvt_pk_bf16_f32 v115, v122, v123
	global_store_dwordx4 v[172:173], v[112:115], off
	s_nop 1
	v_cvt_pk_bf16_f32 v112, v116, v117
	v_cvt_pk_bf16_f32 v113, v118, v119
	v_cvt_pk_bf16_f32 v114, v176, v177
	v_cvt_pk_bf16_f32 v115, v180, v181
	global_store_dwordx4 v[172:173], v[112:115], off offset:256
	s_nop 0
	s_nop 0
	v_or_b32_e32 v112, 32, v144
	v_mad_i64_i32 v[114:115], s[0:1], v174, s51, v[146:147]
	v_lshl_add_u64 v[114:115], v[114:115], 0, v[148:149]
	v_fmamk_f32 v113, v185, 0x3b000000, v171
	v_rsq_f32_e32 v116, v113
	v_ashrrev_i32_e32 v113, 31, v112
	v_lshl_add_u64 v[118:119], v[112:113], 2, s[14:15]
	v_pk_mul_f32 v[110:111], v[110:111], v[116:117] op_sel_hi:[1,0]
	v_pk_mul_f32 v[108:109], v[108:109], v[116:117] op_sel_hi:[1,0]
	v_pk_mul_f32 v[106:107], v[106:107], v[116:117] op_sel_hi:[1,0]
	v_pk_mul_f32 v[104:105], v[104:105], v[116:117] op_sel_hi:[1,0]
	v_pk_mul_f32 v[102:103], v[102:103], v[116:117] op_sel_hi:[1,0]
	v_pk_mul_f32 v[100:101], v[100:101], v[116:117] op_sel_hi:[1,0]
	v_pk_mul_f32 v[120:121], v[98:99], v[116:117] op_sel_hi:[1,0]
	v_pk_mul_f32 v[116:117], v[96:97], v[116:117] op_sel_hi:[1,0]
	v_cvt_pk_bf16_f32 v96, v108, v109
	v_cvt_pk_bf16_f32 v97, v110, v111
	v_cvt_pk_bf16_f32 v98, v104, v105
	v_cvt_pk_bf16_f32 v99, v106, v107
	global_store_dwordx4 v[114:115], v[96:99], off
	s_nop 1
	v_cvt_pk_bf16_f32 v96, v100, v101
	v_cvt_pk_bf16_f32 v97, v102, v103
	v_cvt_pk_bf16_f32 v98, v116, v117
	v_cvt_pk_bf16_f32 v99, v120, v121
	global_store_dwordx4 v[114:115], v[96:99], off offset:256
	s_nop 0
	s_nop 0
	v_or_b32_e32 v96, 48, v144
	v_mad_i64_i32 v[98:99], s[0:1], v112, s51, v[146:147]
	v_lshl_add_u64 v[98:99], v[98:99], 0, v[148:149]
	v_fmamk_f32 v97, v186, 0x3b000000, v171
	v_rsq_f32_e32 v100, v97
	v_ashrrev_i32_e32 v97, 31, v96
	v_lshl_add_u64 v[102:103], v[96:97], 2, s[14:15]
	v_pk_mul_f32 v[94:95], v[94:95], v[100:101] op_sel_hi:[1,0]
	v_pk_mul_f32 v[92:93], v[92:93], v[100:101] op_sel_hi:[1,0]
	v_pk_mul_f32 v[90:91], v[90:91], v[100:101] op_sel_hi:[1,0]
	v_pk_mul_f32 v[88:89], v[88:89], v[100:101] op_sel_hi:[1,0]
	v_pk_mul_f32 v[82:83], v[82:83], v[100:101] op_sel_hi:[1,0]
	v_pk_mul_f32 v[80:81], v[80:81], v[100:101] op_sel_hi:[1,0]
	v_pk_mul_f32 v[104:105], v[74:75], v[100:101] op_sel_hi:[1,0]
	v_pk_mul_f32 v[100:101], v[72:73], v[100:101] op_sel_hi:[1,0]
	v_cvt_pk_bf16_f32 v72, v92, v93
	v_cvt_pk_bf16_f32 v73, v94, v95
	v_cvt_pk_bf16_f32 v74, v88, v89
	v_cvt_pk_bf16_f32 v75, v90, v91
	global_store_dwordx4 v[98:99], v[72:75], off
	s_nop 1
	v_cvt_pk_bf16_f32 v72, v80, v81
	v_cvt_pk_bf16_f32 v73, v82, v83
	v_cvt_pk_bf16_f32 v74, v100, v101
	v_cvt_pk_bf16_f32 v75, v104, v105
	global_store_dwordx4 v[98:99], v[72:75], off offset:256
	s_nop 0
	s_nop 0
	v_mad_i64_i32 v[74:75], s[0:1], v96, s51, v[146:147]
	v_lshl_add_u64 v[74:75], v[74:75], 0, v[148:149]
	v_fmamk_f32 v72, v187, 0x3b000000, v171
	v_rsq_f32_e32 v72, v72
	s_nop 0
	v_pk_mul_f32 v[80:81], v[86:87], v[72:73] op_sel_hi:[1,0]
	v_pk_mul_f32 v[82:83], v[84:85], v[72:73] op_sel_hi:[1,0]
	v_pk_mul_f32 v[78:79], v[78:79], v[72:73] op_sel_hi:[1,0]
	v_pk_mul_f32 v[76:77], v[76:77], v[72:73] op_sel_hi:[1,0]
	v_pk_mul_f32 v[70:71], v[70:71], v[72:73] op_sel_hi:[1,0]
	v_pk_mul_f32 v[68:69], v[68:69], v[72:73] op_sel_hi:[1,0]
; __device__ __forceinline__ unsigned cvt_pk_bf16(float lo, float hi) { unsigned r; asm volatile("v_cvt_pk_bf16_f32 %0, %1, %2" : "=v"(r) : "v"(lo), "v"(hi)); return r; }
;     __device__ __forceinline__ void operator()(const f32x4 (&acc)[2][2][4][2], const Unit& u, int wr, int wc, int fr, int fq) const {
;         const int row0 = u.pm * BM + wr * 64 + fr, col0 = u.pn * BM + wc * 32 + 8 * fq;
; #pragma unroll
;         for (int ai = 0; ai < 2; ++ai)
; #pragma unroll
;             for (int m = 0; m < 4; ++m) { const int row = row0 + ai * HALF + m * 16; bf16_t* rowp = O + (size_t)row * ldc + col0;
;                 const float rs = __builtin_amdgcn_rsqf(ss[row] * inv_n + EPS);
; #pragma unroll
;                 for (int bj = 0; bj < 2; ++bj) { const f32x4 v0 = acc[ai][bj][m][0] * rs, v1 = acc[ai][bj][m][1] * rs;
;                     u32x4 w; w.x = cvt_pk_bf16(v0[0], v0[1]); w.y = cvt_pk_bf16(v0[2], v0[3]); w.z = cvt_pk_bf16(v1[0], v1[1]); w.w = cvt_pk_bf16(v1[2], v1[3]);
;                     *(u32x4*)(rowp + bj * HALF) = w; } }
;     }
	v_pk_mul_f32 v[84:85], v[66:67], v[72:73] op_sel_hi:[1,0]
	v_pk_mul_f32 v[72:73], v[64:65], v[72:73] op_sel_hi:[1,0]
	v_cvt_pk_bf16_f32 v64, v82, v83
	v_cvt_pk_bf16_f32 v65, v80, v81
	v_cvt_pk_bf16_f32 v66, v76, v77
	v_cvt_pk_bf16_f32 v67, v78, v79
	global_store_dwordx4 v[74:75], v[64:67], off
	s_nop 1
	v_cvt_pk_bf16_f32 v64, v68, v69
	v_cvt_pk_bf16_f32 v65, v70, v71
	v_cvt_pk_bf16_f32 v66, v72, v73
	v_cvt_pk_bf16_f32 v67, v84, v85
	global_store_dwordx4 v[74:75], v[64:67], off offset:256
	s_nop 0
	s_nop 0
	v_add_u32_e32 v65, 0x80, v144
	v_mad_i64_i32 v[66:67], s[0:1], v65, s51, v[146:147]
	v_lshl_add_u64 v[66:67], v[66:67], 0, v[148:149]
	v_fmamk_f32 v64, v188, 0x3b000000, v171
	v_rsq_f32_e32 v64, v64
	s_nop 0
	v_pk_mul_f32 v[62:63], v[62:63], v[64:65] op_sel_hi:[1,0]
	v_pk_mul_f32 v[60:61], v[60:61], v[64:65] op_sel_hi:[1,0]
	v_pk_mul_f32 v[58:59], v[58:59], v[64:65] op_sel_hi:[1,0]
	v_pk_mul_f32 v[56:57], v[56:57], v[64:65] op_sel_hi:[1,0]
	v_pk_mul_f32 v[54:55], v[54:55], v[64:65] op_sel_hi:[1,0]
	v_pk_mul_f32 v[52:53], v[52:53], v[64:65] op_sel_hi:[1,0]
	v_pk_mul_f32 v[68:69], v[50:51], v[64:65] op_sel_hi:[1,0]
	v_pk_mul_f32 v[64:65], v[48:49], v[64:65] op_sel_hi:[1,0]
	v_cvt_pk_bf16_f32 v48, v60, v61
	v_cvt_pk_bf16_f32 v49, v62, v63
	v_cvt_pk_bf16_f32 v50, v56, v57
	v_cvt_pk_bf16_f32 v51, v58, v59
	global_store_dwordx4 v[66:67], v[48:51], off
	s_nop 1
	v_cvt_pk_bf16_f32 v48, v52, v53
	v_cvt_pk_bf16_f32 v49, v54, v55
	v_cvt_pk_bf16_f32 v50, v64, v65
	v_cvt_pk_bf16_f32 v51, v68, v69
	global_store_dwordx4 v[66:67], v[48:51], off offset:256
	s_nop 0
	s_nop 0
	v_add_u32_e32 v49, 0x90, v144
	v_mad_i64_i32 v[50:51], s[0:1], v49, s51, v[146:147]
	v_lshl_add_u64 v[50:51], v[50:51], 0, v[148:149]
	v_fmamk_f32 v48, v189, 0x3b000000, v171
	v_rsq_f32_e32 v48, v48
	s_nop 0
	v_pk_mul_f32 v[46:47], v[46:47], v[48:49] op_sel_hi:[1,0]
	v_pk_mul_f32 v[44:45], v[44:45], v[48:49] op_sel_hi:[1,0]
	v_pk_mul_f32 v[42:43], v[42:43], v[48:49] op_sel_hi:[1,0]
	v_pk_mul_f32 v[40:41], v[40:41], v[48:49] op_sel_hi:[1,0]
	v_pk_mul_f32 v[38:39], v[38:39], v[48:49] op_sel_hi:[1,0]
	v_pk_mul_f32 v[36:37], v[36:37], v[48:49] op_sel_hi:[1,0]
	v_pk_mul_f32 v[52:53], v[34:35], v[48:49] op_sel_hi:[1,0]
	v_pk_mul_f32 v[48:49], v[32:33], v[48:49] op_sel_hi:[1,0]
	v_cvt_pk_bf16_f32 v32, v44, v45
	v_cvt_pk_bf16_f32 v33, v46, v47
	v_cvt_pk_bf16_f32 v34, v40, v41
	v_cvt_pk_bf16_f32 v35, v42, v43
	global_store_dwordx4 v[50:51], v[32:35], off
	s_nop 1
	v_cvt_pk_bf16_f32 v32, v36, v37
	v_cvt_pk_bf16_f32 v33, v38, v39
	v_cvt_pk_bf16_f32 v34, v48, v49
	v_cvt_pk_bf16_f32 v35, v52, v53
	global_store_dwordx4 v[50:51], v[32:35], off offset:256
	s_nop 0
	s_nop 0
	v_add_u32_e32 v33, 0xa0, v144
	v_mad_i64_i32 v[34:35], s[0:1], v33, s51, v[146:147]
	v_lshl_add_u64 v[34:35], v[34:35], 0, v[148:149]
	v_fmamk_f32 v32, v190, 0x3b000000, v171
	v_rsq_f32_e32 v32, v32
	s_nop 0
	v_pk_mul_f32 v[30:31], v[30:31], v[32:33] op_sel_hi:[1,0]
	v_pk_mul_f32 v[28:29], v[28:29], v[32:33] op_sel_hi:[1,0]
	v_pk_mul_f32 v[26:27], v[26:27], v[32:33] op_sel_hi:[1,0]
	v_pk_mul_f32 v[24:25], v[24:25], v[32:33] op_sel_hi:[1,0]
	v_pk_mul_f32 v[22:23], v[22:23], v[32:33] op_sel_hi:[1,0]
	v_pk_mul_f32 v[20:21], v[20:21], v[32:33] op_sel_hi:[1,0]
	v_pk_mul_f32 v[36:37], v[18:19], v[32:33] op_sel_hi:[1,0]
	v_pk_mul_f32 v[32:33], v[16:17], v[32:33] op_sel_hi:[1,0]
	v_cvt_pk_bf16_f32 v16, v28, v29
	v_cvt_pk_bf16_f32 v17, v30, v31
	v_cvt_pk_bf16_f32 v18, v24, v25
	v_cvt_pk_bf16_f32 v19, v26, v27
	global_store_dwordx4 v[34:35], v[16:19], off
	s_nop 1
	v_cvt_pk_bf16_f32 v16, v20, v21
	v_cvt_pk_bf16_f32 v17, v22, v23
	v_cvt_pk_bf16_f32 v18, v32, v33
	v_cvt_pk_bf16_f32 v19, v36, v37
	global_store_dwordx4 v[34:35], v[16:19], off offset:256
	s_nop 0
	s_nop 0
	v_add_u32_e32 v17, 0xb0, v144
	v_mad_i64_i32 v[18:19], s[0:1], v17, s51, v[146:147]
	v_lshl_add_u64 v[18:19], v[18:19], 0, v[148:149]
	s_mov_b64 s[0:1], -1
	v_fmamk_f32 v16, v191, 0x3b000000, v171
	v_rsq_f32_e32 v16, v16
	s_nop 0
	v_pk_mul_f32 v[14:15], v[14:15], v[16:17] op_sel_hi:[1,0]
	v_pk_mul_f32 v[12:13], v[12:13], v[16:17] op_sel_hi:[1,0]
	v_pk_mul_f32 v[10:11], v[10:11], v[16:17] op_sel_hi:[1,0]
	v_pk_mul_f32 v[8:9], v[8:9], v[16:17] op_sel_hi:[1,0]
	v_pk_mul_f32 v[6:7], v[6:7], v[16:17] op_sel_hi:[1,0]
	v_pk_mul_f32 v[4:5], v[4:5], v[16:17] op_sel_hi:[1,0]
	v_pk_mul_f32 v[20:21], v[2:3], v[16:17] op_sel_hi:[1,0]
	v_pk_mul_f32 v[16:17], v[0:1], v[16:17] op_sel_hi:[1,0]
	v_cvt_pk_bf16_f32 v0, v12, v13
	v_cvt_pk_bf16_f32 v1, v14, v15
	v_cvt_pk_bf16_f32 v2, v8, v9
	v_cvt_pk_bf16_f32 v3, v10, v11
	global_store_dwordx4 v[18:19], v[0:3], off
	s_nop 1
	v_cvt_pk_bf16_f32 v0, v4, v5
	v_cvt_pk_bf16_f32 v1, v6, v7
	v_cvt_pk_bf16_f32 v2, v16, v17
	v_cvt_pk_bf16_f32 v3, v20, v21
	global_store_dwordx4 v[18:19], v[0:3], off offset:256
	s_cbranch_vccnz .LBB0_329
	s_andn2_b64 vcc, exec, s[10:11]
	s_cbranch_vccnz .LBB0_328
	s_barrier
	s_branch .LBB0_328

; __device__ __forceinline__ unsigned cvt_pk_bf16(float lo, float hi) { unsigned r; asm volatile("v_cvt_pk_bf16_f32 %0, %1, %2" : "=v"(r) : "v"(lo), "v"(hi)); return r; }
;     __device__ __forceinline__ void operator()(const f32x4 (&acc)[2][2][4][2], const Unit& u, int wr, int wc, int fr, int fq) const {
;         const int row0 = u.pm * BM + wr * 64 + fr, col0 = u.pn * BM + wc * 32 + 8 * fq;
; #pragma unroll
;         for (int ai = 0; ai < 2; ++ai)
; #pragma unroll
;             for (int m = 0; m < 4; ++m) { const int row = row0 + ai * HALF + m * 16; bf16_t* rowp = O + (size_t)row * ldc + col0;
;                 const float rs = __builtin_amdgcn_rsqf(ss[row] * inv_n + EPS);
; #pragma unroll
;                 for (int bj = 0; bj < 2; ++bj) { const f32x4 v0 = acc[ai][bj][m][0] * rs, v1 = acc[ai][bj][m][1] * rs;
;                     u32x4 w; w.x = cvt_pk_bf16(v0[0], v0[1]); w.y = cvt_pk_bf16(v0[2], v0[3]); w.z = cvt_pk_bf16(v1[0], v1[1]); w.w = cvt_pk_bf16(v1[2], v1[3]);
;                     *(u32x4*)(rowp + bj * HALF) = w; } }
;     }
.LBB0_362:
	v_lshl_add_u32 v164, s38, 8, v146
	v_ashrrev_i32_e32 v165, 31, v164
	v_lshl_add_u64 v[140:141], v[164:165], 2, s[16:17]
	global_load_dword v184, v[140:141], off
	global_load_dword v185, v[140:141], off offset:64
	global_load_dword v186, v[140:141], off offset:128
	global_load_dword v187, v[140:141], off offset:192
	global_load_dword v188, v[140:141], off offset:512
	global_load_dword v189, v[140:141], off offset:576
	global_load_dword v190, v[140:141], off offset:640
	global_load_dword v191, v[140:141], off offset:704
	v_lshl_or_b32 v142, s76, 8, v148
	v_ashrrev_i32_e32 v143, 31, v142
	v_lshlrev_b64 v[170:171], 1, v[142:143]
	v_lshlrev_b64 v[168:169], 12, v[164:165]
	v_or_b32_e32 v166, 16, v164
	v_ashrrev_i32_e32 v167, 31, v166
	v_readlane_b32 s78, v240, 10
	s_mov_b64 s[0:1], -1
	v_readlane_b32 s79, v240, 11
	s_waitcnt vmcnt(0)
	v_fmamk_f32 v142, v184, 0x3b800000, v163
	v_rsq_f32_e32 v172, v142
	v_lshl_add_u64 v[142:143], s[10:11], 0, v[168:169]
	v_lshl_add_u64 v[142:143], v[142:143], 0, v[170:171]
	v_lshl_add_u64 v[168:169], v[166:167], 2, s[16:17]
	v_pk_mul_f32 v[126:127], v[126:127], v[172:173] op_sel_hi:[1,0]
	v_pk_mul_f32 v[124:125], v[124:125], v[172:173] op_sel_hi:[1,0]
	v_pk_mul_f32 v[122:123], v[122:123], v[172:173] op_sel_hi:[1,0]
	v_pk_mul_f32 v[120:121], v[120:121], v[172:173] op_sel_hi:[1,0]
	v_pk_mul_f32 v[118:119], v[118:119], v[172:173] op_sel_hi:[1,0]
	v_pk_mul_f32 v[116:117], v[116:117], v[172:173] op_sel_hi:[1,0]
	v_pk_mul_f32 v[174:175], v[114:115], v[172:173] op_sel_hi:[1,0]
	v_pk_mul_f32 v[172:173], v[112:113], v[172:173] op_sel_hi:[1,0]
	v_cvt_pk_bf16_f32 v112, v124, v125
	v_cvt_pk_bf16_f32 v113, v126, v127
	v_cvt_pk_bf16_f32 v114, v120, v121
	v_cvt_pk_bf16_f32 v115, v122, v123
	global_store_dwordx4 v[142:143], v[112:115], off
	s_nop 1
	v_cvt_pk_bf16_f32 v112, v116, v117
	v_cvt_pk_bf16_f32 v113, v118, v119
	v_cvt_pk_bf16_f32 v114, v172, v173
	v_cvt_pk_bf16_f32 v115, v174, v175
	global_store_dwordx4 v[142:143], v[112:115], off offset:256
	s_nop 0
	v_fmamk_f32 v116, v185, 0x3b800000, v163
	v_rsq_f32_e32 v116, v116
	v_lshlrev_b64 v[114:115], 12, v[166:167]
	v_or_b32_e32 v112, 32, v164
	v_lshl_add_u64 v[114:115], s[10:11], 0, v[114:115]
	v_ashrrev_i32_e32 v113, 31, v112
	v_lshl_add_u64 v[114:115], v[114:115], 0, v[170:171]
	v_pk_mul_f32 v[110:111], v[110:111], v[116:117] op_sel_hi:[1,0]
	v_pk_mul_f32 v[108:109], v[108:109], v[116:117] op_sel_hi:[1,0]
	v_pk_mul_f32 v[106:107], v[106:107], v[116:117] op_sel_hi:[1,0]
	v_pk_mul_f32 v[104:105], v[104:105], v[116:117] op_sel_hi:[1,0]
	v_pk_mul_f32 v[102:103], v[102:103], v[116:117] op_sel_hi:[1,0]
	v_pk_mul_f32 v[100:101], v[100:101], v[116:117] op_sel_hi:[1,0]
	v_pk_mul_f32 v[120:121], v[98:99], v[116:117] op_sel_hi:[1,0]
	v_pk_mul_f32 v[116:117], v[96:97], v[116:117] op_sel_hi:[1,0]
	v_cvt_pk_bf16_f32 v96, v108, v109
	v_cvt_pk_bf16_f32 v97, v110, v111
	v_cvt_pk_bf16_f32 v98, v104, v105
	v_cvt_pk_bf16_f32 v99, v106, v107
	v_lshl_add_u64 v[118:119], v[112:113], 2, s[16:17]
	global_store_dwordx4 v[114:115], v[96:99], off
	s_nop 1
	v_cvt_pk_bf16_f32 v96, v100, v101
	v_cvt_pk_bf16_f32 v97, v102, v103
	v_cvt_pk_bf16_f32 v98, v116, v117
	v_cvt_pk_bf16_f32 v99, v120, v121
	global_store_dwordx4 v[114:115], v[96:99], off offset:256
	s_nop 0
	v_fmamk_f32 v100, v186, 0x3b800000, v163
	v_rsq_f32_e32 v100, v100
	v_lshlrev_b64 v[98:99], 12, v[112:113]
	v_or_b32_e32 v96, 48, v164
	v_lshl_add_u64 v[98:99], s[10:11], 0, v[98:99]
	v_ashrrev_i32_e32 v97, 31, v96
	v_lshl_add_u64 v[98:99], v[98:99], 0, v[170:171]
	v_pk_mul_f32 v[94:95], v[94:95], v[100:101] op_sel_hi:[1,0]
	v_pk_mul_f32 v[92:93], v[92:93], v[100:101] op_sel_hi:[1,0]
	v_pk_mul_f32 v[90:91], v[90:91], v[100:101] op_sel_hi:[1,0]
	v_pk_mul_f32 v[88:89], v[88:89], v[100:101] op_sel_hi:[1,0]
	v_pk_mul_f32 v[82:83], v[82:83], v[100:101] op_sel_hi:[1,0]
	v_pk_mul_f32 v[80:81], v[80:81], v[100:101] op_sel_hi:[1,0]
	v_pk_mul_f32 v[104:105], v[78:79], v[100:101] op_sel_hi:[1,0]
	v_pk_mul_f32 v[100:101], v[76:77], v[100:101] op_sel_hi:[1,0]
	v_cvt_pk_bf16_f32 v76, v92, v93
	v_cvt_pk_bf16_f32 v77, v94, v95
	v_cvt_pk_bf16_f32 v78, v88, v89
	v_cvt_pk_bf16_f32 v79, v90, v91
	v_lshl_add_u64 v[102:103], v[96:97], 2, s[16:17]
	global_store_dwordx4 v[98:99], v[76:79], off
	s_nop 1
	v_cvt_pk_bf16_f32 v76, v80, v81
	v_cvt_pk_bf16_f32 v77, v82, v83
	v_cvt_pk_bf16_f32 v78, v100, v101
	v_cvt_pk_bf16_f32 v79, v104, v105
	global_store_dwordx4 v[98:99], v[76:79], off offset:256
	s_nop 0
	s_nop 0
	v_lshlrev_b64 v[78:79], 12, v[96:97]
	v_lshl_add_u64 v[78:79], s[10:11], 0, v[78:79]
	v_lshl_add_u64 v[78:79], v[78:79], 0, v[170:171]
	v_fmamk_f32 v76, v187, 0x3b800000, v163
	v_rsq_f32_e32 v76, v76
	s_nop 0
	v_pk_mul_f32 v[80:81], v[86:87], v[76:77] op_sel_hi:[1,0]
	v_pk_mul_f32 v[82:83], v[84:85], v[76:77] op_sel_hi:[1,0]
	v_pk_mul_f32 v[74:75], v[74:75], v[76:77] op_sel_hi:[1,0]
	v_pk_mul_f32 v[72:73], v[72:73], v[76:77] op_sel_hi:[1,0]
	v_pk_mul_f32 v[70:71], v[70:71], v[76:77] op_sel_hi:[1,0]
; __device__ __forceinline__ unsigned cvt_pk_bf16(float lo, float hi) { unsigned r; asm volatile("v_cvt_pk_bf16_f32 %0, %1, %2" : "=v"(r) : "v"(lo), "v"(hi)); return r; }
;     __device__ __forceinline__ void operator()(const f32x4 (&acc)[2][2][4][2], const Unit& u, int wr, int wc, int fr, int fq) const {
;         const int row0 = u.pm * BM + wr * 64 + fr, col0 = u.pn * BM + wc * 32 + 8 * fq;
; #pragma unroll
;         for (int ai = 0; ai < 2; ++ai)
; #pragma unroll
;             for (int m = 0; m < 4; ++m) { const int row = row0 + ai * HALF + m * 16; bf16_t* rowp = O + (size_t)row * ldc + col0;
;                 const float rs = __builtin_amdgcn_rsqf(ss[row] * inv_n + EPS);
; #pragma unroll
;                 for (int bj = 0; bj < 2; ++bj) { const f32x4 v0 = acc[ai][bj][m][0] * rs, v1 = acc[ai][bj][m][1] * rs;
;                     u32x4 w; w.x = cvt_pk_bf16(v0[0], v0[1]); w.y = cvt_pk_bf16(v0[2], v0[3]); w.z = cvt_pk_bf16(v1[0], v1[1]); w.w = cvt_pk_bf16(v1[2], v1[3]);
;                     *(u32x4*)(rowp + bj * HALF) = w; } }
;     }
	v_pk_mul_f32 v[68:69], v[68:69], v[76:77] op_sel_hi:[1,0]
	v_pk_mul_f32 v[84:85], v[66:67], v[76:77] op_sel_hi:[1,0]
	v_pk_mul_f32 v[76:77], v[64:65], v[76:77] op_sel_hi:[1,0]
	v_cvt_pk_bf16_f32 v64, v82, v83
	v_cvt_pk_bf16_f32 v65, v80, v81
	v_cvt_pk_bf16_f32 v66, v72, v73
	v_cvt_pk_bf16_f32 v67, v74, v75
	global_store_dwordx4 v[78:79], v[64:67], off
	s_nop 1
	v_cvt_pk_bf16_f32 v64, v68, v69
	v_cvt_pk_bf16_f32 v65, v70, v71
	v_cvt_pk_bf16_f32 v66, v76, v77
	v_cvt_pk_bf16_f32 v67, v84, v85
	global_store_dwordx4 v[78:79], v[64:67], off offset:256
	s_nop 0
	v_add_co_u32_e32 v68, vcc, s70, v142
	v_lshl_add_u64 v[64:65], v[142:143], 0, s[14:15]
	s_nop 0
	v_addc_co_u32_e32 v69, vcc, 0, v143, vcc
	v_fmamk_f32 v66, v188, 0x3b800000, v163
	v_rsq_f32_e32 v66, v66
	s_nop 0
	v_pk_mul_f32 v[62:63], v[62:63], v[66:67] op_sel_hi:[1,0]
	v_pk_mul_f32 v[60:61], v[60:61], v[66:67] op_sel_hi:[1,0]
	v_pk_mul_f32 v[58:59], v[58:59], v[66:67] op_sel_hi:[1,0]
	v_pk_mul_f32 v[56:57], v[56:57], v[66:67] op_sel_hi:[1,0]
	v_pk_mul_f32 v[54:55], v[54:55], v[66:67] op_sel_hi:[1,0]
	v_pk_mul_f32 v[52:53], v[52:53], v[66:67] op_sel_hi:[1,0]
	v_pk_mul_f32 v[70:71], v[50:51], v[66:67] op_sel_hi:[1,0]
	v_pk_mul_f32 v[66:67], v[48:49], v[66:67] op_sel_hi:[1,0]
	v_cvt_pk_bf16_f32 v48, v60, v61
	v_cvt_pk_bf16_f32 v49, v62, v63
	v_cvt_pk_bf16_f32 v50, v56, v57
	v_cvt_pk_bf16_f32 v51, v58, v59
	global_store_dwordx4 v[68:69], v[48:51], off
	s_nop 1
	v_cvt_pk_bf16_f32 v48, v52, v53
	v_cvt_pk_bf16_f32 v49, v54, v55
	v_cvt_pk_bf16_f32 v50, v66, v67
	v_cvt_pk_bf16_f32 v51, v70, v71
	global_store_dwordx4 v[64:65], v[48:51], off offset:256
	s_nop 0
	v_add_co_u32_e32 v52, vcc, s71, v142
	v_lshl_add_u64 v[48:49], v[142:143], 0, s[22:23]
	s_nop 0
	v_addc_co_u32_e32 v53, vcc, 0, v143, vcc
	v_fmamk_f32 v50, v189, 0x3b800000, v163
	v_rsq_f32_e32 v50, v50
	s_nop 0
	v_pk_mul_f32 v[46:47], v[46:47], v[50:51] op_sel_hi:[1,0]
	v_pk_mul_f32 v[44:45], v[44:45], v[50:51] op_sel_hi:[1,0]
	v_pk_mul_f32 v[42:43], v[42:43], v[50:51] op_sel_hi:[1,0]
	v_pk_mul_f32 v[40:41], v[40:41], v[50:51] op_sel_hi:[1,0]
	v_pk_mul_f32 v[38:39], v[38:39], v[50:51] op_sel_hi:[1,0]
	v_pk_mul_f32 v[36:37], v[36:37], v[50:51] op_sel_hi:[1,0]
	v_pk_mul_f32 v[54:55], v[34:35], v[50:51] op_sel_hi:[1,0]
	v_pk_mul_f32 v[50:51], v[32:33], v[50:51] op_sel_hi:[1,0]
	v_cvt_pk_bf16_f32 v32, v44, v45
	v_cvt_pk_bf16_f32 v33, v46, v47
	v_cvt_pk_bf16_f32 v34, v40, v41
	v_cvt_pk_bf16_f32 v35, v42, v43
	global_store_dwordx4 v[52:53], v[32:35], off
	s_nop 1
	v_cvt_pk_bf16_f32 v32, v36, v37
	v_cvt_pk_bf16_f32 v33, v38, v39
	v_cvt_pk_bf16_f32 v34, v50, v51
	v_cvt_pk_bf16_f32 v35, v54, v55
	global_store_dwordx4 v[48:49], v[32:35], off offset:256
	s_nop 0
	v_add_co_u32_e32 v36, vcc, s74, v142
	v_lshl_add_u64 v[32:33], v[142:143], 0, s[24:25]
	s_nop 0
	v_addc_co_u32_e32 v37, vcc, 0, v143, vcc
	s_andn2_b64 vcc, exec, s[4:5]
	v_fmamk_f32 v34, v190, 0x3b800000, v163
	v_rsq_f32_e32 v34, v34
	s_nop 0
	v_pk_mul_f32 v[30:31], v[30:31], v[34:35] op_sel_hi:[1,0]
	v_pk_mul_f32 v[28:29], v[28:29], v[34:35] op_sel_hi:[1,0]
	v_pk_mul_f32 v[26:27], v[26:27], v[34:35] op_sel_hi:[1,0]
	v_pk_mul_f32 v[24:25], v[24:25], v[34:35] op_sel_hi:[1,0]
	v_pk_mul_f32 v[22:23], v[22:23], v[34:35] op_sel_hi:[1,0]
	v_pk_mul_f32 v[20:21], v[20:21], v[34:35] op_sel_hi:[1,0]
	v_pk_mul_f32 v[38:39], v[18:19], v[34:35] op_sel_hi:[1,0]
	v_pk_mul_f32 v[34:35], v[16:17], v[34:35] op_sel_hi:[1,0]
	v_cvt_pk_bf16_f32 v16, v28, v29
	v_cvt_pk_bf16_f32 v17, v30, v31
	v_cvt_pk_bf16_f32 v18, v24, v25
	v_cvt_pk_bf16_f32 v19, v26, v27
	global_store_dwordx4 v[36:37], v[16:19], off
	s_nop 1
	v_cvt_pk_bf16_f32 v16, v20, v21
	v_cvt_pk_bf16_f32 v17, v22, v23
	v_cvt_pk_bf16_f32 v18, v34, v35
	v_cvt_pk_bf16_f32 v19, v38, v39
	global_store_dwordx4 v[32:33], v[16:19], off offset:256
	s_nop 0
	v_add_co_u32_e64 v20, s[4:5], s75, v142
	v_lshl_add_u64 v[16:17], v[142:143], 0, s[26:27]
	s_nop 0
	v_addc_co_u32_e64 v21, s[4:5], 0, v143, s[4:5]
	v_fmamk_f32 v18, v191, 0x3b800000, v163
	v_rsq_f32_e32 v18, v18
	s_nop 0
	v_pk_mul_f32 v[14:15], v[14:15], v[18:19] op_sel_hi:[1,0]
	v_pk_mul_f32 v[12:13], v[12:13], v[18:19] op_sel_hi:[1,0]
	v_pk_mul_f32 v[10:11], v[10:11], v[18:19] op_sel_hi:[1,0]
	v_pk_mul_f32 v[8:9], v[8:9], v[18:19] op_sel_hi:[1,0]
	v_pk_mul_f32 v[6:7], v[6:7], v[18:19] op_sel_hi:[1,0]
	v_pk_mul_f32 v[4:5], v[4:5], v[18:19] op_sel_hi:[1,0]
	v_pk_mul_f32 v[22:23], v[2:3], v[18:19] op_sel_hi:[1,0]
	v_pk_mul_f32 v[18:19], v[0:1], v[18:19] op_sel_hi:[1,0]
	v_cvt_pk_bf16_f32 v0, v12, v13
	v_cvt_pk_bf16_f32 v1, v14, v15
	v_cvt_pk_bf16_f32 v2, v8, v9
	v_cvt_pk_bf16_f32 v3, v10, v11
	global_store_dwordx4 v[20:21], v[0:3], off
	s_nop 1
	v_cvt_pk_bf16_f32 v0, v4, v5
	v_cvt_pk_bf16_f32 v1, v6, v7
	v_cvt_pk_bf16_f32 v2, v18, v19
	v_cvt_pk_bf16_f32 v3, v22, v23
	global_store_dwordx4 v[16:17], v[0:3], off offset:256
	s_cbranch_vccnz .LBB0_351
	s_andn2_b64 vcc, exec, s[12:13]
	s_cbranch_vccnz .LBB0_350
	s_barrier
	s_branch .LBB0_350

; __device__ __forceinline__ unsigned cvt_pk_bf16(float lo, float hi) { unsigned r; asm volatile("v_cvt_pk_bf16_f32 %0, %1, %2" : "=v"(r) : "v"(lo), "v"(hi)); return r; }
; __device__ __forceinline__ int crow(int r, int hi) { return (r & 3) + 8 * (r >> 2) + 4 * hi; }
; template <class C>
; __device__ __forceinline__ void block(const BlockRef& cur, const BlockRef& nxt, int skv, char* lds, Seam<C>& S, const float* gq, const float2* rt) {
;     ...
;     if (hi == 0) li_l[r32] = l_reg; asm volatile("s_waitcnt lgkmcnt(0)" ::: "memory");
;     float rli[16];
; #pragma unroll
;     for (int r = 0; r < 16; ++r) rli[r] = __builtin_amdgcn_rcpf(li_l[crow(r, hi)]);
;     bf16_t* Ow = cur.O + (size_t)(wid * QBLK) * C::OS;
; #pragma unroll
;     for (int r = 0; r < 16; ++r) { const int orow = crow(r, hi);
; #pragma unroll
;         for (int d0 = 0; d0 < 4; ++d0) { const float v = o[d0][r] * rli[r];
;             const float vn = __shfl_xor(v, 1);
;             if ((r32 & 1) == 0) *(unsigned*)(Ow + (size_t)orow * C::OS + d0 * 32 + r32) = cvt_pk_bf16(v, vn); } }
;     asm volatile("s_waitcnt lgkmcnt(0)" ::: "memory");
.LBB0_484:
	s_and_saveexec_b64 s[0:1], s[4:5]
	ds_write_b32 v201, v205
	s_or_b64 exec, exec, s[0:1]
	s_waitcnt lgkmcnt(0)
	ds_read_b128 v[76:79], v203
	ds_read_b128 v[72:75], v203 offset:32
	ds_read_b128 v[68:71], v203 offset:64
	ds_read_b128 v[64:67], v203 offset:96
	s_ashr_i32 s71, s70, 31
	s_lshl_b64 s[0:1], s[70:71], 12
	s_add_u32 s0, s36, s0
	s_addc_u32 s1, s37, s1
	v_and_b32_e32 v82, 1, v197
	v_lshlrev_b32_e32 v180, 1, v196
	v_cmp_eq_u32_e64 s[4:5], 0, v82
	v_lshl_add_u64 v[80:81], s[0:1], 0, v[180:181]
	v_lshlrev_b32_e32 v180, 14, v195
	v_lshl_add_u64 v[80:81], v[80:81], 0, v[180:181]
	v_mul_u32_u24_e32 v82, 62, v82
	v_mov_b32_e32 v83, 0
	v_lshl_add_u64 v[80:81], v[80:81], 0, v[82:83]
	v_readlane_b32 s78, v240, 10
	v_readlane_b32 s86, v240, 27
	v_readlane_b32 s79, v240, 11
	v_and_b32_e32 v86, 64, v193
	v_xor_b32_e32 v87, 1, v193
	v_add_u32_e32 v86, 64, v86
	v_cmp_lt_i32_e32 vcc, v87, v86
	s_nop 1
	v_cndmask_b32_e32 v87, v193, v87, vcc
	v_lshlrev_b32_e32 v172, 2, v87
	s_mov_b64 s[6:7], 0x1000
	s_mov_b64 s[8:9], 0x5000
	v_mov_b32_e32 v84, 0x1000302
	v_mov_b32_e32 v85, 0x3020100
	v_cndmask_b32_e64 v84, v84, v85, s[4:5]
	s_waitcnt lgkmcnt(0)
	v_rcp_f32_e32 v76, v76
	v_rcp_f32_e32 v77, v77
	v_rcp_f32_e32 v78, v78
	v_rcp_f32_e32 v79, v79
	v_rcp_f32_e32 v72, v72
	v_rcp_f32_e32 v73, v73
	v_rcp_f32_e32 v74, v74
	v_rcp_f32_e32 v75, v75
	v_rcp_f32_e32 v68, v68
	v_rcp_f32_e32 v69, v69
	v_rcp_f32_e32 v70, v70
	v_rcp_f32_e32 v71, v71
	v_rcp_f32_e32 v64, v64
	v_rcp_f32_e32 v65, v65
	v_rcp_f32_e32 v66, v66
	v_rcp_f32_e32 v67, v67
	s_nop 0
	v_cndmask_b32_e64 v86, v16, v48, s[4:5]
	v_cndmask_b32_e64 v87, v48, v16, s[4:5]
	v_cndmask_b32_e64 v88, v32, v0, s[4:5]
	v_cndmask_b32_e64 v89, v0, v32, s[4:5]
	v_mul_f32_dpp v90, v86, v76 quad_perm:[1,0,3,2] row_mask:0xf bank_mask:0xf
	v_mul_f32_dpp v91, v88, v76 quad_perm:[1,0,3,2] row_mask:0xf bank_mask:0xf
	v_mul_f32_e32 v87, v87, v76
	v_mul_f32_e32 v89, v89, v76
	v_cvt_pk_bf16_f32 v92, v87, v90
	v_cvt_pk_bf16_f32 v93, v89, v91
	v_perm_b32 v92, v92, v92, v84
	v_perm_b32 v93, v93, v93, v84
	global_store_dword v[80:81], v92, off
	global_store_dword v[80:81], v93, off offset:128
	v_lshl_add_u64 v[80:81], v[80:81], 0, s[6:7]
	v_cndmask_b32_e64 v164, v17, v49, s[4:5]
	v_cndmask_b32_e64 v165, v49, v17, s[4:5]
	v_cndmask_b32_e64 v166, v33, v1, s[4:5]
	v_cndmask_b32_e64 v167, v1, v33, s[4:5]
	v_mul_f32_dpp v168, v164, v77 quad_perm:[1,0,3,2] row_mask:0xf bank_mask:0xf
	v_mul_f32_dpp v169, v166, v77 quad_perm:[1,0,3,2] row_mask:0xf bank_mask:0xf
	v_mul_f32_e32 v165, v165, v77
	v_mul_f32_e32 v167, v167, v77
	v_cvt_pk_bf16_f32 v170, v165, v168
	v_cvt_pk_bf16_f32 v171, v167, v169
	v_perm_b32 v170, v170, v170, v84
	v_perm_b32 v171, v171, v171, v84
	global_store_dword v[80:81], v170, off
	global_store_dword v[80:81], v171, off offset:128
	v_lshl_add_u64 v[80:81], v[80:81], 0, s[6:7]
	v_cndmask_b32_e64 v86, v18, v50, s[4:5]
	v_cndmask_b32_e64 v87, v50, v18, s[4:5]
	v_cndmask_b32_e64 v88, v34, v2, s[4:5]
	v_cndmask_b32_e64 v89, v2, v34, s[4:5]
	v_mul_f32_dpp v90, v86, v78 quad_perm:[1,0,3,2] row_mask:0xf bank_mask:0xf
	v_mul_f32_dpp v91, v88, v78 quad_perm:[1,0,3,2] row_mask:0xf bank_mask:0xf
	v_mul_f32_e32 v87, v87, v78
	v_mul_f32_e32 v89, v89, v78
	v_cvt_pk_bf16_f32 v92, v87, v90
	v_cvt_pk_bf16_f32 v93, v89, v91
	v_perm_b32 v92, v92, v92, v84
	v_perm_b32 v93, v93, v93, v84
	global_store_dword v[80:81], v92, off
	global_store_dword v[80:81], v93, off offset:128
	v_lshl_add_u64 v[80:81], v[80:81], 0, s[6:7]
	v_cndmask_b32_e64 v164, v19, v51, s[4:5]
	v_cndmask_b32_e64 v165, v51, v19, s[4:5]
	v_cndmask_b32_e64 v166, v35, v3, s[4:5]
	v_cndmask_b32_e64 v167, v3, v35, s[4:5]
	v_mul_f32_dpp v168, v164, v79 quad_perm:[1,0,3,2] row_mask:0xf bank_mask:0xf
	v_mul_f32_dpp v169, v166, v79 quad_perm:[1,0,3,2] row_mask:0xf bank_mask:0xf
	v_mul_f32_e32 v165, v165, v79
	v_mul_f32_e32 v167, v167, v79
	v_cvt_pk_bf16_f32 v170, v165, v168
	v_cvt_pk_bf16_f32 v171, v167, v169
	v_perm_b32 v170, v170, v170, v84
	v_perm_b32 v171, v171, v171, v84
	global_store_dword v[80:81], v170, off
	global_store_dword v[80:81], v171, off offset:128
	v_lshl_add_u64 v[80:81], v[80:81], 0, s[8:9]
	v_cndmask_b32_e64 v86, v20, v52, s[4:5]
	v_cndmask_b32_e64 v87, v52, v20, s[4:5]
	v_cndmask_b32_e64 v88, v36, v4, s[4:5]
	v_cndmask_b32_e64 v89, v4, v36, s[4:5]
	v_mul_f32_dpp v90, v86, v72 quad_perm:[1,0,3,2] row_mask:0xf bank_mask:0xf
	v_mul_f32_dpp v91, v88, v72 quad_perm:[1,0,3,2] row_mask:0xf bank_mask:0xf
	v_mul_f32_e32 v87, v87, v72
	v_mul_f32_e32 v89, v89, v72
	v_cvt_pk_bf16_f32 v92, v87, v90
	v_cvt_pk_bf16_f32 v93, v89, v91
	v_perm_b32 v92, v92, v92, v84
	v_perm_b32 v93, v93, v93, v84
	global_store_dword v[80:81], v92, off
	global_store_dword v[80:81], v93, off offset:128
	v_lshl_add_u64 v[80:81], v[80:81], 0, s[6:7]
	v_cndmask_b32_e64 v164, v21, v53, s[4:5]
	v_cndmask_b32_e64 v165, v53, v21, s[4:5]
	v_cndmask_b32_e64 v166, v37, v5, s[4:5]
	v_cndmask_b32_e64 v167, v5, v37, s[4:5]
	v_mul_f32_dpp v168, v164, v73 quad_perm:[1,0,3,2] row_mask:0xf bank_mask:0xf
	v_mul_f32_dpp v169, v166, v73 quad_perm:[1,0,3,2] row_mask:0xf bank_mask:0xf
	v_mul_f32_e32 v165, v165, v73
	v_mul_f32_e32 v167, v167, v73
	v_cvt_pk_bf16_f32 v170, v165, v168
	v_cvt_pk_bf16_f32 v171, v167, v169
	v_perm_b32 v170, v170, v170, v84
	v_perm_b32 v171, v171, v171, v84
	global_store_dword v[80:81], v170, off
	global_store_dword v[80:81], v171, off offset:128
	v_lshl_add_u64 v[80:81], v[80:81], 0, s[6:7]
	v_cndmask_b32_e64 v86, v22, v54, s[4:5]
	v_cndmask_b32_e64 v87, v54, v22, s[4:5]
	v_cndmask_b32_e64 v88, v38, v6, s[4:5]
	v_cndmask_b32_e64 v89, v6, v38, s[4:5]
; __device__ __forceinline__ unsigned cvt_pk_bf16(float lo, float hi) { unsigned r; asm volatile("v_cvt_pk_bf16_f32 %0, %1, %2" : "=v"(r) : "v"(lo), "v"(hi)); return r; }
; __device__ __forceinline__ int crow(int r, int hi) { return (r & 3) + 8 * (r >> 2) + 4 * hi; }
; template <class C>
; __device__ __forceinline__ void block(const BlockRef& cur, const BlockRef& nxt, int skv, char* lds, Seam<C>& S, const float* gq, const float2* rt) {
;     ...
;     if (hi == 0) li_l[r32] = l_reg; asm volatile("s_waitcnt lgkmcnt(0)" ::: "memory");
;     float rli[16];
; #pragma unroll
;     for (int r = 0; r < 16; ++r) rli[r] = __builtin_amdgcn_rcpf(li_l[crow(r, hi)]);
;     bf16_t* Ow = cur.O + (size_t)(wid * QBLK) * C::OS;
; #pragma unroll
;     for (int r = 0; r < 16; ++r) { const int orow = crow(r, hi);
; #pragma unroll
;         for (int d0 = 0; d0 < 4; ++d0) { const float v = o[d0][r] * rli[r];
;             const float vn = __shfl_xor(v, 1);
;             if ((r32 & 1) == 0) *(unsigned*)(Ow + (size_t)orow * C::OS + d0 * 32 + r32) = cvt_pk_bf16(v, vn); } }
;     asm volatile("s_waitcnt lgkmcnt(0)" ::: "memory");
	v_mul_f32_dpp v90, v86, v74 quad_perm:[1,0,3,2] row_mask:0xf bank_mask:0xf
	v_mul_f32_dpp v91, v88, v74 quad_perm:[1,0,3,2] row_mask:0xf bank_mask:0xf
	v_mul_f32_e32 v87, v87, v74
	v_mul_f32_e32 v89, v89, v74
	v_cvt_pk_bf16_f32 v92, v87, v90
	v_cvt_pk_bf16_f32 v93, v89, v91
	v_perm_b32 v92, v92, v92, v84
	v_perm_b32 v93, v93, v93, v84
	global_store_dword v[80:81], v92, off
	global_store_dword v[80:81], v93, off offset:128
	v_lshl_add_u64 v[80:81], v[80:81], 0, s[6:7]
	v_cndmask_b32_e64 v164, v23, v55, s[4:5]
	v_cndmask_b32_e64 v165, v55, v23, s[4:5]
	v_cndmask_b32_e64 v166, v39, v7, s[4:5]
	v_cndmask_b32_e64 v167, v7, v39, s[4:5]
	v_mul_f32_dpp v168, v164, v75 quad_perm:[1,0,3,2] row_mask:0xf bank_mask:0xf
	v_mul_f32_dpp v169, v166, v75 quad_perm:[1,0,3,2] row_mask:0xf bank_mask:0xf
	v_mul_f32_e32 v165, v165, v75
	v_mul_f32_e32 v167, v167, v75
	v_cvt_pk_bf16_f32 v170, v165, v168
	v_cvt_pk_bf16_f32 v171, v167, v169
	v_perm_b32 v170, v170, v170, v84
	v_perm_b32 v171, v171, v171, v84
	global_store_dword v[80:81], v170, off
	global_store_dword v[80:81], v171, off offset:128
	v_lshl_add_u64 v[80:81], v[80:81], 0, s[8:9]
	v_cndmask_b32_e64 v86, v24, v56, s[4:5]
	v_cndmask_b32_e64 v87, v56, v24, s[4:5]
	v_cndmask_b32_e64 v88, v40, v8, s[4:5]
	v_cndmask_b32_e64 v89, v8, v40, s[4:5]
	v_mul_f32_dpp v90, v86, v68 quad_perm:[1,0,3,2] row_mask:0xf bank_mask:0xf
	v_mul_f32_dpp v91, v88, v68 quad_perm:[1,0,3,2] row_mask:0xf bank_mask:0xf
	v_mul_f32_e32 v87, v87, v68
	v_mul_f32_e32 v89, v89, v68
	v_cvt_pk_bf16_f32 v92, v87, v90
	v_cvt_pk_bf16_f32 v93, v89, v91
	v_perm_b32 v92, v92, v92, v84
	v_perm_b32 v93, v93, v93, v84
	global_store_dword v[80:81], v92, off
	global_store_dword v[80:81], v93, off offset:128
	v_lshl_add_u64 v[80:81], v[80:81], 0, s[6:7]
	v_cndmask_b32_e64 v164, v25, v57, s[4:5]
	v_cndmask_b32_e64 v165, v57, v25, s[4:5]
	v_cndmask_b32_e64 v166, v41, v9, s[4:5]
	v_cndmask_b32_e64 v167, v9, v41, s[4:5]
	v_mul_f32_dpp v168, v164, v69 quad_perm:[1,0,3,2] row_mask:0xf bank_mask:0xf
	v_mul_f32_dpp v169, v166, v69 quad_perm:[1,0,3,2] row_mask:0xf bank_mask:0xf
	v_mul_f32_e32 v165, v165, v69
	v_mul_f32_e32 v167, v167, v69
	v_cvt_pk_bf16_f32 v170, v165, v168
	v_cvt_pk_bf16_f32 v171, v167, v169
	v_perm_b32 v170, v170, v170, v84
	v_perm_b32 v171, v171, v171, v84
	global_store_dword v[80:81], v170, off
	global_store_dword v[80:81], v171, off offset:128
	v_lshl_add_u64 v[80:81], v[80:81], 0, s[6:7]
	v_cndmask_b32_e64 v86, v26, v58, s[4:5]
	v_cndmask_b32_e64 v87, v58, v26, s[4:5]
	v_cndmask_b32_e64 v88, v42, v10, s[4:5]
	v_cndmask_b32_e64 v89, v10, v42, s[4:5]
	v_mul_f32_dpp v90, v86, v70 quad_perm:[1,0,3,2] row_mask:0xf bank_mask:0xf
	v_mul_f32_dpp v91, v88, v70 quad_perm:[1,0,3,2] row_mask:0xf bank_mask:0xf
	v_mul_f32_e32 v87, v87, v70
	v_mul_f32_e32 v89, v89, v70
	v_cvt_pk_bf16_f32 v92, v87, v90
	v_cvt_pk_bf16_f32 v93, v89, v91
	v_perm_b32 v92, v92, v92, v84
	v_perm_b32 v93, v93, v93, v84
	global_store_dword v[80:81], v92, off
	global_store_dword v[80:81], v93, off offset:128
	v_lshl_add_u64 v[80:81], v[80:81], 0, s[6:7]
	v_cndmask_b32_e64 v164, v27, v59, s[4:5]
	v_cndmask_b32_e64 v165, v59, v27, s[4:5]
	v_cndmask_b32_e64 v166, v43, v11, s[4:5]
	v_cndmask_b32_e64 v167, v11, v43, s[4:5]
	v_mul_f32_dpp v168, v164, v71 quad_perm:[1,0,3,2] row_mask:0xf bank_mask:0xf
	v_mul_f32_dpp v169, v166, v71 quad_perm:[1,0,3,2] row_mask:0xf bank_mask:0xf
	v_mul_f32_e32 v165, v165, v71
	v_mul_f32_e32 v167, v167, v71
	v_cvt_pk_bf16_f32 v170, v165, v168
	v_cvt_pk_bf16_f32 v171, v167, v169
	v_perm_b32 v170, v170, v170, v84
	v_perm_b32 v171, v171, v171, v84
	global_store_dword v[80:81], v170, off
	global_store_dword v[80:81], v171, off offset:128
	v_lshl_add_u64 v[80:81], v[80:81], 0, s[8:9]
	v_cndmask_b32_e64 v86, v28, v60, s[4:5]
	v_cndmask_b32_e64 v87, v60, v28, s[4:5]
	v_cndmask_b32_e64 v88, v44, v12, s[4:5]
	v_cndmask_b32_e64 v89, v12, v44, s[4:5]
	v_mul_f32_dpp v90, v86, v64 quad_perm:[1,0,3,2] row_mask:0xf bank_mask:0xf
	v_mul_f32_dpp v91, v88, v64 quad_perm:[1,0,3,2] row_mask:0xf bank_mask:0xf
	v_mul_f32_e32 v87, v87, v64
	v_mul_f32_e32 v89, v89, v64
	v_cvt_pk_bf16_f32 v92, v87, v90
	v_cvt_pk_bf16_f32 v93, v89, v91
	v_perm_b32 v92, v92, v92, v84
	v_perm_b32 v93, v93, v93, v84
	global_store_dword v[80:81], v92, off
	global_store_dword v[80:81], v93, off offset:128
	v_lshl_add_u64 v[80:81], v[80:81], 0, s[6:7]
	v_cndmask_b32_e64 v164, v29, v61, s[4:5]
	v_cndmask_b32_e64 v165, v61, v29, s[4:5]
	v_cndmask_b32_e64 v166, v45, v13, s[4:5]
	v_cndmask_b32_e64 v167, v13, v45, s[4:5]
	v_mul_f32_dpp v168, v164, v65 quad_perm:[1,0,3,2] row_mask:0xf bank_mask:0xf
	v_mul_f32_dpp v169, v166, v65 quad_perm:[1,0,3,2] row_mask:0xf bank_mask:0xf
	v_mul_f32_e32 v165, v165, v65
	v_mul_f32_e32 v167, v167, v65
	v_cvt_pk_bf16_f32 v170, v165, v168
	v_cvt_pk_bf16_f32 v171, v167, v169
	v_perm_b32 v170, v170, v170, v84
	v_perm_b32 v171, v171, v171, v84
	global_store_dword v[80:81], v170, off
	global_store_dword v[80:81], v171, off offset:128
	v_lshl_add_u64 v[80:81], v[80:81], 0, s[6:7]
	v_cndmask_b32_e64 v86, v30, v62, s[4:5]
	v_cndmask_b32_e64 v87, v62, v30, s[4:5]
	v_cndmask_b32_e64 v88, v46, v14, s[4:5]
	v_cndmask_b32_e64 v89, v14, v46, s[4:5]
	v_mul_f32_dpp v90, v86, v66 quad_perm:[1,0,3,2] row_mask:0xf bank_mask:0xf
	v_mul_f32_dpp v91, v88, v66 quad_perm:[1,0,3,2] row_mask:0xf bank_mask:0xf
	v_mul_f32_e32 v87, v87, v66
	v_mul_f32_e32 v89, v89, v66
	v_cvt_pk_bf16_f32 v92, v87, v90
	v_cvt_pk_bf16_f32 v93, v89, v91
	v_perm_b32 v92, v92, v92, v84
	v_perm_b32 v93, v93, v93, v84
	global_store_dword v[80:81], v92, off
	global_store_dword v[80:81], v93, off offset:128
	v_lshl_add_u64 v[80:81], v[80:81], 0, s[6:7]
	v_cndmask_b32_e64 v164, v31, v63, s[4:5]
	v_cndmask_b32_e64 v165, v63, v31, s[4:5]
	v_cndmask_b32_e64 v166, v47, v15, s[4:5]
	v_cndmask_b32_e64 v167, v15, v47, s[4:5]
	v_mul_f32_dpp v168, v164, v67 quad_perm:[1,0,3,2] row_mask:0xf bank_mask:0xf
	v_mul_f32_dpp v169, v166, v67 quad_perm:[1,0,3,2] row_mask:0xf bank_mask:0xf
	v_mul_f32_e32 v165, v165, v67
	v_mul_f32_e32 v167, v167, v67
	v_cvt_pk_bf16_f32 v170, v165, v168
	v_cvt_pk_bf16_f32 v171, v167, v169
	v_perm_b32 v170, v170, v170, v84
	v_perm_b32 v171, v171, v171, v84
	global_store_dword v[80:81], v170, off
	global_store_dword v[80:81], v171, off offset:128
	s_mov_b64 s[0:1], exec
	s_branch .LBB0_459

; __device__ __forceinline__ unsigned cvt_pk_bf16(float lo, float hi) { unsigned r; asm volatile("v_cvt_pk_bf16_f32 %0, %1, %2" : "=v"(r) : "v"(lo), "v"(hi)); return r; }
;     __device__ __forceinline__ void operator()(const f32x4 (&acc)[2][2][4][2], const Unit& u, int wr, int wc, int fr, int fq) const {
;         const int row0 = u.pm * BM + wr * 64 + fr, col0 = u.pn * BM + wc * 32 + 8 * fq;
; #pragma unroll
;         for (int ai = 0; ai < 2; ++ai)
; #pragma unroll
;             for (int m = 0; m < 4; ++m) { const int row = row0 + ai * HALF + m * 16; bf16_t* rowp = O + (size_t)row * ldc + col0;
;                 const float rs = __builtin_amdgcn_rsqf(ss[row] * inv_n + EPS);
; #pragma unroll
;                 for (int bj = 0; bj < 2; ++bj) { const f32x4 v0 = acc[ai][bj][m][0] * rs, v1 = acc[ai][bj][m][1] * rs;
;                     u32x4 w; w.x = cvt_pk_bf16(v0[0], v0[1]); w.y = cvt_pk_bf16(v0[2], v0[3]); w.z = cvt_pk_bf16(v1[0], v1[1]); w.w = cvt_pk_bf16(v1[2], v1[3]);
;                     *(u32x4*)(rowp + bj * HALF) = w; } }
;     }
.LBB0_935:
	v_lshl_add_u32 v144, s26, 8, v152
	v_ashrrev_i32_e32 v145, 31, v144
	v_lshl_add_u64 v[150:151], v[144:145], 2, s[12:13]
	global_load_dword v184, v[150:151], off
	global_load_dword v185, v[150:151], off offset:64
	global_load_dword v186, v[150:151], off offset:128
	global_load_dword v187, v[150:151], off offset:192
	global_load_dword v188, v[150:151], off offset:512
	global_load_dword v189, v[150:151], off offset:576
	global_load_dword v190, v[150:151], off offset:640
	global_load_dword v191, v[150:151], off offset:704
	v_lshl_or_b32 v148, s50, 8, v154
	v_mov_b64_e32 v[146:147], s[10:11]
	v_ashrrev_i32_e32 v149, 31, v148
	v_mad_i64_i32 v[160:161], s[0:1], v144, s49, v[146:147]
	v_or_b32_e32 v162, 16, v144
	v_lshlrev_b64 v[148:149], 1, v[148:149]
	v_ashrrev_i32_e32 v163, 31, v162
	v_lshl_add_u64 v[160:161], v[160:161], 0, v[148:149]
	v_lshl_add_u64 v[166:167], v[162:163], 2, s[12:13]
	s_andn2_b64 vcc, exec, s[4:5]
	s_waitcnt vmcnt(0)
	v_fmamk_f32 v145, v184, 0x3a000000, v158
	v_rsq_f32_e32 v164, v145
	s_nop 0
	v_pk_mul_f32 v[126:127], v[126:127], v[164:165] op_sel_hi:[1,0]
	v_pk_mul_f32 v[124:125], v[124:125], v[164:165] op_sel_hi:[1,0]
	v_pk_mul_f32 v[122:123], v[122:123], v[164:165] op_sel_hi:[1,0]
	v_pk_mul_f32 v[120:121], v[120:121], v[164:165] op_sel_hi:[1,0]
	v_pk_mul_f32 v[118:119], v[118:119], v[164:165] op_sel_hi:[1,0]
	v_pk_mul_f32 v[116:117], v[116:117], v[164:165] op_sel_hi:[1,0]
	v_pk_mul_f32 v[168:169], v[114:115], v[164:165] op_sel_hi:[1,0]
	v_pk_mul_f32 v[164:165], v[112:113], v[164:165] op_sel_hi:[1,0]
	v_cvt_pk_bf16_f32 v112, v124, v125
	v_cvt_pk_bf16_f32 v113, v126, v127
	v_cvt_pk_bf16_f32 v114, v120, v121
	v_cvt_pk_bf16_f32 v115, v122, v123
	global_store_dwordx4 v[160:161], v[112:115], off
	s_nop 1
	v_cvt_pk_bf16_f32 v112, v116, v117
	v_cvt_pk_bf16_f32 v113, v118, v119
	v_cvt_pk_bf16_f32 v114, v164, v165
	v_cvt_pk_bf16_f32 v115, v168, v169
	global_store_dwordx4 v[160:161], v[112:115], off offset:256
	s_nop 0
	s_nop 0
	v_or_b32_e32 v112, 32, v144
	v_mad_i64_i32 v[114:115], s[0:1], v162, s49, v[146:147]
	v_lshl_add_u64 v[114:115], v[114:115], 0, v[148:149]
	v_fmamk_f32 v113, v185, 0x3a000000, v158
	v_rsq_f32_e32 v116, v113
	v_ashrrev_i32_e32 v113, 31, v112
	v_lshl_add_u64 v[118:119], v[112:113], 2, s[12:13]
	v_pk_mul_f32 v[110:111], v[110:111], v[116:117] op_sel_hi:[1,0]
	v_pk_mul_f32 v[108:109], v[108:109], v[116:117] op_sel_hi:[1,0]
	v_pk_mul_f32 v[106:107], v[106:107], v[116:117] op_sel_hi:[1,0]
	v_pk_mul_f32 v[104:105], v[104:105], v[116:117] op_sel_hi:[1,0]
	v_pk_mul_f32 v[102:103], v[102:103], v[116:117] op_sel_hi:[1,0]
	v_pk_mul_f32 v[100:101], v[100:101], v[116:117] op_sel_hi:[1,0]
	v_pk_mul_f32 v[120:121], v[98:99], v[116:117] op_sel_hi:[1,0]
	v_pk_mul_f32 v[116:117], v[96:97], v[116:117] op_sel_hi:[1,0]
	v_cvt_pk_bf16_f32 v96, v108, v109
	v_cvt_pk_bf16_f32 v97, v110, v111
	v_cvt_pk_bf16_f32 v98, v104, v105
	v_cvt_pk_bf16_f32 v99, v106, v107
	global_store_dwordx4 v[114:115], v[96:99], off
	s_nop 1
	v_cvt_pk_bf16_f32 v96, v100, v101
	v_cvt_pk_bf16_f32 v97, v102, v103
	v_cvt_pk_bf16_f32 v98, v116, v117
	v_cvt_pk_bf16_f32 v99, v120, v121
	global_store_dwordx4 v[114:115], v[96:99], off offset:256
	s_nop 0
	s_nop 0
	v_or_b32_e32 v96, 48, v144
	v_mad_i64_i32 v[98:99], s[0:1], v112, s49, v[146:147]
	v_lshl_add_u64 v[98:99], v[98:99], 0, v[148:149]
	v_fmamk_f32 v97, v186, 0x3a000000, v158
	v_rsq_f32_e32 v100, v97
	v_ashrrev_i32_e32 v97, 31, v96
	v_lshl_add_u64 v[102:103], v[96:97], 2, s[12:13]
	v_pk_mul_f32 v[94:95], v[94:95], v[100:101] op_sel_hi:[1,0]
	v_pk_mul_f32 v[92:93], v[92:93], v[100:101] op_sel_hi:[1,0]
	v_pk_mul_f32 v[90:91], v[90:91], v[100:101] op_sel_hi:[1,0]
	v_pk_mul_f32 v[88:89], v[88:89], v[100:101] op_sel_hi:[1,0]
	v_pk_mul_f32 v[82:83], v[82:83], v[100:101] op_sel_hi:[1,0]
	v_pk_mul_f32 v[80:81], v[80:81], v[100:101] op_sel_hi:[1,0]
	v_pk_mul_f32 v[104:105], v[74:75], v[100:101] op_sel_hi:[1,0]
	v_pk_mul_f32 v[100:101], v[72:73], v[100:101] op_sel_hi:[1,0]
	v_cvt_pk_bf16_f32 v72, v92, v93
	v_cvt_pk_bf16_f32 v73, v94, v95
	v_cvt_pk_bf16_f32 v74, v88, v89
	v_cvt_pk_bf16_f32 v75, v90, v91
	global_store_dwordx4 v[98:99], v[72:75], off
	s_nop 1
	v_cvt_pk_bf16_f32 v72, v80, v81
	v_cvt_pk_bf16_f32 v73, v82, v83
	v_cvt_pk_bf16_f32 v74, v100, v101
	v_cvt_pk_bf16_f32 v75, v104, v105
	global_store_dwordx4 v[98:99], v[72:75], off offset:256
	s_nop 0
	s_nop 0
	v_mad_i64_i32 v[74:75], s[0:1], v96, s49, v[146:147]
	v_lshl_add_u64 v[74:75], v[74:75], 0, v[148:149]
	v_fmamk_f32 v72, v187, 0x3a000000, v158
	v_rsq_f32_e32 v72, v72
	s_nop 0
	v_pk_mul_f32 v[80:81], v[86:87], v[72:73] op_sel_hi:[1,0]
	v_pk_mul_f32 v[82:83], v[84:85], v[72:73] op_sel_hi:[1,0]
	v_pk_mul_f32 v[78:79], v[78:79], v[72:73] op_sel_hi:[1,0]
	v_pk_mul_f32 v[76:77], v[76:77], v[72:73] op_sel_hi:[1,0]
	v_pk_mul_f32 v[70:71], v[70:71], v[72:73] op_sel_hi:[1,0]
	v_pk_mul_f32 v[68:69], v[68:69], v[72:73] op_sel_hi:[1,0]
; __device__ __forceinline__ unsigned cvt_pk_bf16(float lo, float hi) { unsigned r; asm volatile("v_cvt_pk_bf16_f32 %0, %1, %2" : "=v"(r) : "v"(lo), "v"(hi)); return r; }
;     __device__ __forceinline__ void operator()(const f32x4 (&acc)[2][2][4][2], const Unit& u, int wr, int wc, int fr, int fq) const {
;         const int row0 = u.pm * BM + wr * 64 + fr, col0 = u.pn * BM + wc * 32 + 8 * fq;
; #pragma unroll
;         for (int ai = 0; ai < 2; ++ai)
; #pragma unroll
;             for (int m = 0; m < 4; ++m) { const int row = row0 + ai * HALF + m * 16; bf16_t* rowp = O + (size_t)row * ldc + col0;
;                 const float rs = __builtin_amdgcn_rsqf(ss[row] * inv_n + EPS);
; #pragma unroll
;                 for (int bj = 0; bj < 2; ++bj) { const f32x4 v0 = acc[ai][bj][m][0] * rs, v1 = acc[ai][bj][m][1] * rs;
;                     u32x4 w; w.x = cvt_pk_bf16(v0[0], v0[1]); w.y = cvt_pk_bf16(v0[2], v0[3]); w.z = cvt_pk_bf16(v1[0], v1[1]); w.w = cvt_pk_bf16(v1[2], v1[3]);
;                     *(u32x4*)(rowp + bj * HALF) = w; } }
;     }
	v_pk_mul_f32 v[84:85], v[66:67], v[72:73] op_sel_hi:[1,0]
	v_pk_mul_f32 v[72:73], v[64:65], v[72:73] op_sel_hi:[1,0]
	v_cvt_pk_bf16_f32 v64, v82, v83
	v_cvt_pk_bf16_f32 v65, v80, v81
	v_cvt_pk_bf16_f32 v66, v76, v77
	v_cvt_pk_bf16_f32 v67, v78, v79
	global_store_dwordx4 v[74:75], v[64:67], off
	s_nop 1
	v_cvt_pk_bf16_f32 v64, v68, v69
	v_cvt_pk_bf16_f32 v65, v70, v71
	v_cvt_pk_bf16_f32 v66, v72, v73
	v_cvt_pk_bf16_f32 v67, v84, v85
	global_store_dwordx4 v[74:75], v[64:67], off offset:256
	s_nop 0
	s_nop 0
	v_add_u32_e32 v65, 0x80, v144
	v_mad_i64_i32 v[66:67], s[0:1], v65, s49, v[146:147]
	v_lshl_add_u64 v[66:67], v[66:67], 0, v[148:149]
	v_fmamk_f32 v64, v188, 0x3a000000, v158
	v_rsq_f32_e32 v64, v64
	s_nop 0
	v_pk_mul_f32 v[62:63], v[62:63], v[64:65] op_sel_hi:[1,0]
	v_pk_mul_f32 v[60:61], v[60:61], v[64:65] op_sel_hi:[1,0]
	v_pk_mul_f32 v[58:59], v[58:59], v[64:65] op_sel_hi:[1,0]
	v_pk_mul_f32 v[56:57], v[56:57], v[64:65] op_sel_hi:[1,0]
	v_pk_mul_f32 v[54:55], v[54:55], v[64:65] op_sel_hi:[1,0]
	v_pk_mul_f32 v[52:53], v[52:53], v[64:65] op_sel_hi:[1,0]
	v_pk_mul_f32 v[68:69], v[50:51], v[64:65] op_sel_hi:[1,0]
	v_pk_mul_f32 v[64:65], v[48:49], v[64:65] op_sel_hi:[1,0]
	v_cvt_pk_bf16_f32 v48, v60, v61
	v_cvt_pk_bf16_f32 v49, v62, v63
	v_cvt_pk_bf16_f32 v50, v56, v57
	v_cvt_pk_bf16_f32 v51, v58, v59
	global_store_dwordx4 v[66:67], v[48:51], off
	s_nop 1
	v_cvt_pk_bf16_f32 v48, v52, v53
	v_cvt_pk_bf16_f32 v49, v54, v55
	v_cvt_pk_bf16_f32 v50, v64, v65
	v_cvt_pk_bf16_f32 v51, v68, v69
	global_store_dwordx4 v[66:67], v[48:51], off offset:256
	s_nop 0
	s_nop 0
	v_add_u32_e32 v49, 0x90, v144
	v_mad_i64_i32 v[50:51], s[0:1], v49, s49, v[146:147]
	v_lshl_add_u64 v[50:51], v[50:51], 0, v[148:149]
	v_fmamk_f32 v48, v189, 0x3a000000, v158
	v_rsq_f32_e32 v48, v48
	s_nop 0
	v_pk_mul_f32 v[46:47], v[46:47], v[48:49] op_sel_hi:[1,0]
	v_pk_mul_f32 v[44:45], v[44:45], v[48:49] op_sel_hi:[1,0]
	v_pk_mul_f32 v[42:43], v[42:43], v[48:49] op_sel_hi:[1,0]
	v_pk_mul_f32 v[40:41], v[40:41], v[48:49] op_sel_hi:[1,0]
	v_pk_mul_f32 v[38:39], v[38:39], v[48:49] op_sel_hi:[1,0]
	v_pk_mul_f32 v[36:37], v[36:37], v[48:49] op_sel_hi:[1,0]
	v_pk_mul_f32 v[52:53], v[34:35], v[48:49] op_sel_hi:[1,0]
	v_pk_mul_f32 v[48:49], v[32:33], v[48:49] op_sel_hi:[1,0]
	v_cvt_pk_bf16_f32 v32, v44, v45
	v_cvt_pk_bf16_f32 v33, v46, v47
	v_cvt_pk_bf16_f32 v34, v40, v41
	v_cvt_pk_bf16_f32 v35, v42, v43
	global_store_dwordx4 v[50:51], v[32:35], off
	s_nop 1
	v_cvt_pk_bf16_f32 v32, v36, v37
	v_cvt_pk_bf16_f32 v33, v38, v39
	v_cvt_pk_bf16_f32 v34, v48, v49
	v_cvt_pk_bf16_f32 v35, v52, v53
	global_store_dwordx4 v[50:51], v[32:35], off offset:256
	s_nop 0
	s_nop 0
	v_add_u32_e32 v33, 0xa0, v144
	v_mad_i64_i32 v[34:35], s[0:1], v33, s49, v[146:147]
	v_lshl_add_u64 v[34:35], v[34:35], 0, v[148:149]
	v_fmamk_f32 v32, v190, 0x3a000000, v158
	v_rsq_f32_e32 v32, v32
	s_nop 0
	v_pk_mul_f32 v[30:31], v[30:31], v[32:33] op_sel_hi:[1,0]
	v_pk_mul_f32 v[28:29], v[28:29], v[32:33] op_sel_hi:[1,0]
	v_pk_mul_f32 v[26:27], v[26:27], v[32:33] op_sel_hi:[1,0]
	v_pk_mul_f32 v[24:25], v[24:25], v[32:33] op_sel_hi:[1,0]
	v_pk_mul_f32 v[22:23], v[22:23], v[32:33] op_sel_hi:[1,0]
	v_pk_mul_f32 v[20:21], v[20:21], v[32:33] op_sel_hi:[1,0]
	v_pk_mul_f32 v[36:37], v[18:19], v[32:33] op_sel_hi:[1,0]
	v_pk_mul_f32 v[32:33], v[16:17], v[32:33] op_sel_hi:[1,0]
	v_cvt_pk_bf16_f32 v16, v28, v29
	v_cvt_pk_bf16_f32 v17, v30, v31
	v_cvt_pk_bf16_f32 v18, v24, v25
	v_cvt_pk_bf16_f32 v19, v26, v27
	global_store_dwordx4 v[34:35], v[16:19], off
	s_nop 1
	v_cvt_pk_bf16_f32 v16, v20, v21
	v_cvt_pk_bf16_f32 v17, v22, v23
	v_cvt_pk_bf16_f32 v18, v32, v33
	v_cvt_pk_bf16_f32 v19, v36, v37
	global_store_dwordx4 v[34:35], v[16:19], off offset:256
	s_nop 0
	s_nop 0
	v_add_u32_e32 v17, 0xb0, v144
	v_mad_i64_i32 v[18:19], s[0:1], v17, s49, v[146:147]
	v_lshl_add_u64 v[18:19], v[18:19], 0, v[148:149]
	s_mov_b64 s[0:1], -1
	v_fmamk_f32 v16, v191, 0x3a000000, v158
	v_rsq_f32_e32 v16, v16
	s_nop 0
	v_pk_mul_f32 v[14:15], v[14:15], v[16:17] op_sel_hi:[1,0]
	v_pk_mul_f32 v[12:13], v[12:13], v[16:17] op_sel_hi:[1,0]
	v_pk_mul_f32 v[10:11], v[10:11], v[16:17] op_sel_hi:[1,0]
	v_pk_mul_f32 v[8:9], v[8:9], v[16:17] op_sel_hi:[1,0]
	v_pk_mul_f32 v[6:7], v[6:7], v[16:17] op_sel_hi:[1,0]
	v_pk_mul_f32 v[4:5], v[4:5], v[16:17] op_sel_hi:[1,0]
	v_pk_mul_f32 v[20:21], v[2:3], v[16:17] op_sel_hi:[1,0]
	v_pk_mul_f32 v[16:17], v[0:1], v[16:17] op_sel_hi:[1,0]
	v_cvt_pk_bf16_f32 v0, v12, v13
	v_cvt_pk_bf16_f32 v1, v14, v15
	v_cvt_pk_bf16_f32 v2, v8, v9
	v_cvt_pk_bf16_f32 v3, v10, v11
	global_store_dwordx4 v[18:19], v[0:3], off
	s_nop 1
	v_cvt_pk_bf16_f32 v0, v4, v5
	v_cvt_pk_bf16_f32 v1, v6, v7
	v_cvt_pk_bf16_f32 v2, v16, v17
	v_cvt_pk_bf16_f32 v3, v20, v21
	global_store_dwordx4 v[18:19], v[0:3], off offset:256
	s_cbranch_vccnz .LBB0_928
	s_andn2_b64 vcc, exec, s[8:9]
	s_cbranch_vccnz .LBB0_927
	s_barrier
	s_branch .LBB0_927
